# top-k bisection: cross-half count sum via v_permlane32_swap instead of ds_bpermute + wait (one LDS round trip less per round)
# speedup vs baseline: 1.0072x; 1.0072x over previous
; DI void a1_task(unsigned char* shm, const bf16_t* prm, const bf16_t* prt, unsigned* mask, int b, int qt, const int tid) {
;     ...
;             const unsigned cand = T | (1u << bit);
;             int c = 0;
; #pragma unroll
;             for (int jt = 0; jt < 8; ++jt) {
;                 if (jt < nheld) {
; #pragma unroll
;                     for (int i = 0; i < 16; ++i) c += (key[jt][i] >= cand) ? 1 : 0;
;                 }
;             }
;             c += __shfl_xor(c, 32);
;             if (h == 0 && c) atomicAdd(&cnt[(31 - bit) * 32 + r], (unsigned)c);
;             __syncthreads();
;             const unsigned tot = cnt[(31 - bit) * 32 + r];
;             if (!done) { if (tot >= 256u) T = cand; if (tot == 256u) done = true; }
;             if (__ballot(!done) == 0ull) break;
.LBB0_477:
	v_mov_b32_e32 v20, v19
	s_nop 1
	v_permlane32_swap_b32_e32 v20, v19
	v_add_u32_e32 v19, v20, v19
	v_cmp_ne_u32_e32 vcc, 0, v19
	s_and_b64 s[54:55], s[58:59], vcc
	s_and_saveexec_b64 s[0:1], s[54:55]
	s_cbranch_execz .LBB0_460
	ds_add_u32 v3, v19
	s_branch .LBB0_460
